# phase 2 mixed order, variant: the other half of the workgroups runs 3 attention rounds, conv, 1 round
# speedup vs baseline: 1.0192x; 1.0005x over previous
.LBB0_1072:
	s_cmp_gt_i32 s66, 1
	s_mov_b64 s[0:1], -1
	s_cbranch_scc0 .LBB0_1115
	s_mov_b32 s98, 0x300
	s_bitcmp1_b32 s99, 3
	s_cselect_b32 s98, 0x100, s98

.Lcv_nn7:
	s_add_u32 s6, s6, 0x200
	s_cmp_lt_u32 s6, 0x400
	s_cbranch_scc1 .Lcv_tile
	v_readlane_b32 s0, v115, 0
	v_readlane_b32 s1, v115, 1
	v_readlane_b32 s2, v115, 2
	v_readlane_b32 s3, v115, 3
	v_readlane_b32 s4, v115, 4
	v_readlane_b32 s5, v115, 5
	v_readlane_b32 s6, v115, 6
	v_readlane_b32 s7, v115, 7
	v_readlane_b32 s8, v115, 8
	v_readlane_b32 s9, v115, 9
	v_readlane_b32 s10, v115, 10
	v_readlane_b32 s11, v115, 11
	v_readlane_b32 s12, v115, 12
	v_readlane_b32 s13, v115, 13
	v_readlane_b32 s14, v115, 14
	v_readlane_b32 s15, v115, 15
	v_readlane_b32 s16, v115, 16
	v_readlane_b32 s17, v115, 17
	v_readlane_b32 s18, v115, 18
	v_readlane_b32 s19, v115, 19
	v_readlane_b32 s20, v115, 20
	v_readlane_b32 s21, v115, 21
	v_readlane_b32 s22, v115, 22
	v_readlane_b32 s23, v115, 23
	v_readlane_b32 s24, v115, 24
	v_readlane_b32 s25, v115, 25
	v_readlane_b32 s26, v115, 26
	v_readlane_b32 s27, v115, 27
	v_readlane_b32 s28, v115, 28
	v_readlane_b32 s29, v115, 29
	v_readlane_b32 s30, v115, 30
	v_readlane_b32 s31, v115, 31
	v_readlane_b32 s32, v115, 32
	v_readlane_b32 s33, v115, 33
	v_readlane_b32 s34, v115, 34
	v_readlane_b32 s35, v115, 35
	v_readlane_b32 s36, v115, 36
	v_readlane_b32 s37, v115, 37
	v_readlane_b32 s38, v115, 38
	v_readlane_b32 s39, v115, 39
	v_readlane_b32 s40, v115, 40
	v_readlane_b32 s41, v115, 41
	v_readlane_b32 s42, v115, 42
	v_readlane_b32 s43, v115, 43
	v_readlane_b32 s44, v115, 44
	v_readlane_b32 s45, v115, 45
	v_readlane_b32 s46, v115, 46
	v_readlane_b32 s47, v115, 47
	s_bfe_u32 vcc_lo, s98, 0x80008
	s_cmp_lt_u32 vcc_lo, 4
	s_cbranch_scc0 .Lp2_done
	s_or_b32 s98, vcc_lo, 0x10400
	s_branch .Lp2_na
